# phase0: silu(c) and adaLN mod GEMV loads issued up-front (32 in flight) instead of 8 serialized round trips
# speedup vs baseline: 1.0087x; 1.0087x over previous
.LBB0_7:
	s_mov_b64 s[8:9], 0x1000
	global_load_dword v20, v[2:3], off
	global_load_dword v21, v[2:3], off offset:2048
	v_lshl_add_u64 v[6:7], v[2:3], 0, s[8:9]
	global_load_dword v22, v[6:7], off
	global_load_dword v23, v[6:7], off offset:2048
	v_lshl_add_u64 v[6:7], v[6:7], 0, s[8:9]
	global_load_dword v24, v[6:7], off
	global_load_dword v25, v[6:7], off offset:2048
	v_lshl_add_u64 v[6:7], v[6:7], 0, s[8:9]
	global_load_dword v26, v[6:7], off
	global_load_dword v27, v[6:7], off offset:2048
	s_waitcnt vmcnt(0)
	v_mul_f32_e32 v28, 0xbfb8aa3b, v20
	v_mul_f32_e32 v29, 0xbfb8aa3b, v21
	v_mul_f32_e32 v30, 0xbfb8aa3b, v22
	v_mul_f32_e32 v31, 0xbfb8aa3b, v23
	v_mul_f32_e32 v32, 0xbfb8aa3b, v24
	v_mul_f32_e32 v33, 0xbfb8aa3b, v25
	v_mul_f32_e32 v34, 0xbfb8aa3b, v26
	v_mul_f32_e32 v35, 0xbfb8aa3b, v27
	v_exp_f32_e32 v28, v28
	v_exp_f32_e32 v29, v29
	v_exp_f32_e32 v30, v30
	v_exp_f32_e32 v31, v31
	v_exp_f32_e32 v32, v32
	v_exp_f32_e32 v33, v33
	v_exp_f32_e32 v34, v34
	v_exp_f32_e32 v35, v35
	v_add_f32_e32 v28, 1.0, v28
	v_add_f32_e32 v29, 1.0, v29
	v_add_f32_e32 v30, 1.0, v30
	v_add_f32_e32 v31, 1.0, v31
	v_add_f32_e32 v32, 1.0, v32
	v_add_f32_e32 v33, 1.0, v33
	v_add_f32_e32 v34, 1.0, v34
	v_add_f32_e32 v35, 1.0, v35
	v_rcp_f32_e32 v28, v28
	v_rcp_f32_e32 v29, v29
	v_rcp_f32_e32 v30, v30
	v_rcp_f32_e32 v31, v31
	v_rcp_f32_e32 v32, v32
	v_rcp_f32_e32 v33, v33
	v_rcp_f32_e32 v34, v34
	v_rcp_f32_e32 v35, v35
	v_mul_f32_e32 v20, v20, v28
	v_mul_f32_e32 v21, v21, v29
	v_mul_f32_e32 v22, v22, v30
	v_mul_f32_e32 v23, v23, v31
	v_mul_f32_e32 v24, v24, v32
	v_mul_f32_e32 v25, v25, v33
	v_mul_f32_e32 v26, v26, v34
	v_mul_f32_e32 v27, v27, v35
	ds_write_b32 v4, v20
	ds_write_b32 v4, v21 offset:2048
	ds_write_b32 v4, v22 offset:4096
	ds_write_b32 v4, v23 offset:6144
	ds_write_b32 v4, v24 offset:8192
	ds_write_b32 v4, v25 offset:10240
	ds_write_b32 v4, v26 offset:12288
	ds_write_b32 v4, v27 offset:14336

.LBB0_11:
	s_mul_i32 s6, s34, 24
	s_ashr_i32 s7, s6, 31
	v_lshl_add_u64 v[8:9], s[6:7], 2, v[4:5]
	v_mov_b32_e32 v47, v41
	s_mov_b32 s14, 0
	v_mov_b32_e32 v10, 0
	v_mov_b32_e32 v11, v3
	v_mov_b32_e32 v12, 0
	v_mov_b32_e32 v13, v3
	v_min_u32_e32 v80, 23, v67
	v_lshlrev_b32_e32 v80, 2, v80
	v_mov_b32_e32 v81, 0
	v_lshl_add_u64 v[82:83], s[6:7], 2, v[80:81]
	v_lshl_add_u64 v[82:83], s[52:53], 0, v[82:83]
	v_add_u32_e32 v84, -14, v41
	v_mul_u32_u24_e64 v84, v84, s33
	v_mov_b32_e32 v85, 0
	v_lshl_add_u64 v[82:83], v[84:85], 0, v[82:83]
	s_mov_b64 s[14:15], 0xc000
	v_add_u32_e32 v84, 0x12000, v35
	global_load_dword v86, v[82:83], off nt
	v_lshl_add_u64 v[82:83], v[82:83], 0, s[14:15]
	global_load_dword v87, v[82:83], off nt
	v_lshl_add_u64 v[82:83], v[82:83], 0, s[14:15]
	global_load_dword v88, v[82:83], off nt
	v_lshl_add_u64 v[82:83], v[82:83], 0, s[14:15]
	global_load_dword v89, v[82:83], off nt
	v_lshl_add_u64 v[82:83], v[82:83], 0, s[14:15]
	global_load_dword v90, v[82:83], off nt
	v_lshl_add_u64 v[82:83], v[82:83], 0, s[14:15]
	global_load_dword v91, v[82:83], off nt
	v_lshl_add_u64 v[82:83], v[82:83], 0, s[14:15]
	global_load_dword v92, v[82:83], off nt
	v_lshl_add_u64 v[82:83], v[82:83], 0, s[14:15]
	global_load_dword v93, v[82:83], off nt
	v_lshl_add_u64 v[82:83], v[82:83], 0, s[14:15]
	global_load_dword v94, v[82:83], off nt
	v_lshl_add_u64 v[82:83], v[82:83], 0, s[14:15]
	global_load_dword v95, v[82:83], off nt
	v_lshl_add_u64 v[82:83], v[82:83], 0, s[14:15]
	global_load_dword v96, v[82:83], off nt
	v_lshl_add_u64 v[82:83], v[82:83], 0, s[14:15]
	global_load_dword v97, v[82:83], off nt
	v_lshl_add_u64 v[82:83], v[82:83], 0, s[14:15]
	global_load_dword v98, v[82:83], off nt
	v_lshl_add_u64 v[82:83], v[82:83], 0, s[14:15]
	global_load_dword v99, v[82:83], off nt
	v_lshl_add_u64 v[82:83], v[82:83], 0, s[14:15]
	global_load_dword v100, v[82:83], off nt
	v_lshl_add_u64 v[82:83], v[82:83], 0, s[14:15]
	global_load_dword v101, v[82:83], off nt
	v_lshl_add_u64 v[82:83], v[82:83], 0, s[14:15]
	global_load_dword v102, v[82:83], off nt
	v_lshl_add_u64 v[82:83], v[82:83], 0, s[14:15]
	global_load_dword v103, v[82:83], off nt
	v_lshl_add_u64 v[82:83], v[82:83], 0, s[14:15]
	global_load_dword v104, v[82:83], off nt
	v_lshl_add_u64 v[82:83], v[82:83], 0, s[14:15]
	global_load_dword v105, v[82:83], off nt
	v_lshl_add_u64 v[82:83], v[82:83], 0, s[14:15]
	global_load_dword v106, v[82:83], off nt
	v_lshl_add_u64 v[82:83], v[82:83], 0, s[14:15]
	global_load_dword v107, v[82:83], off nt
	v_lshl_add_u64 v[82:83], v[82:83], 0, s[14:15]
	global_load_dword v108, v[82:83], off nt
	v_lshl_add_u64 v[82:83], v[82:83], 0, s[14:15]
	global_load_dword v109, v[82:83], off nt
	v_lshl_add_u64 v[82:83], v[82:83], 0, s[14:15]
	global_load_dword v110, v[82:83], off nt
	v_lshl_add_u64 v[82:83], v[82:83], 0, s[14:15]
	global_load_dword v111, v[82:83], off nt
	v_lshl_add_u64 v[82:83], v[82:83], 0, s[14:15]
	global_load_dword v112, v[82:83], off nt
	v_lshl_add_u64 v[82:83], v[82:83], 0, s[14:15]
	global_load_dword v113, v[82:83], off nt
	v_lshl_add_u64 v[82:83], v[82:83], 0, s[14:15]
	global_load_dword v114, v[82:83], off nt
	v_lshl_add_u64 v[82:83], v[82:83], 0, s[14:15]
	global_load_dword v115, v[82:83], off nt
	v_lshl_add_u64 v[82:83], v[82:83], 0, s[14:15]
	global_load_dword v116, v[82:83], off nt
	v_lshl_add_u64 v[82:83], v[82:83], 0, s[14:15]
	global_load_dword v117, v[82:83], off nt
	v_lshl_add_u64 v[82:83], v[82:83], 0, s[14:15]
	v_add_u32_e32 v85, 0, v84
	ds_read2st64_b32 v[150:151], v85 offset1:16
	ds_read2st64_b32 v[152:153], v85 offset0:32 offset1:48
	v_add_u32_e32 v85, 8, v84
	ds_read2st64_b32 v[154:155], v85 offset1:16
	ds_read2st64_b32 v[156:157], v85 offset0:32 offset1:48
	v_add_u32_e32 v85, 16, v84
	ds_read2st64_b32 v[158:159], v85 offset1:16
	ds_read2st64_b32 v[160:161], v85 offset0:32 offset1:48
	v_add_u32_e32 v85, 24, v84
	ds_read2st64_b32 v[162:163], v85 offset1:16
	ds_read2st64_b32 v[164:165], v85 offset0:32 offset1:48
	v_add_u32_e32 v85, 32, v84
	ds_read2st64_b32 v[166:167], v85 offset1:16
	ds_read2st64_b32 v[168:169], v85 offset0:32 offset1:48
	v_add_u32_e32 v85, 40, v84
	ds_read2st64_b32 v[170:171], v85 offset1:16
	ds_read2st64_b32 v[172:173], v85 offset0:32 offset1:48
	v_add_u32_e32 v85, 48, v84
	ds_read2st64_b32 v[174:175], v85 offset1:16
	ds_read2st64_b32 v[176:177], v85 offset0:32 offset1:48
	v_add_u32_e32 v85, 56, v84
	ds_read2st64_b32 v[178:179], v85 offset1:16
	ds_read2st64_b32 v[180:181], v85 offset0:32 offset1:48
	s_waitcnt lgkmcnt(0)
	v_add_u32_e32 v85, 64, v84
	ds_read2st64_b32 v[182:183], v85 offset1:16
	ds_read2st64_b32 v[184:185], v85 offset0:32 offset1:48
	v_add_u32_e32 v85, 72, v84
	ds_read2st64_b32 v[186:187], v85 offset1:16
	ds_read2st64_b32 v[188:189], v85 offset0:32 offset1:48
	v_add_u32_e32 v85, 80, v84
	ds_read2st64_b32 v[190:191], v85 offset1:16
	ds_read2st64_b32 v[192:193], v85 offset0:32 offset1:48
	v_add_u32_e32 v85, 88, v84
	ds_read2st64_b32 v[194:195], v85 offset1:16
	ds_read2st64_b32 v[196:197], v85 offset0:32 offset1:48
	v_add_u32_e32 v85, 96, v84
	ds_read2st64_b32 v[198:199], v85 offset1:16
	ds_read2st64_b32 v[200:201], v85 offset0:32 offset1:48
	v_add_u32_e32 v85, 104, v84
	ds_read2st64_b32 v[202:203], v85 offset1:16
	ds_read2st64_b32 v[204:205], v85 offset0:32 offset1:48
	v_add_u32_e32 v85, 112, v84
	ds_read2st64_b32 v[206:207], v85 offset1:16
	ds_read2st64_b32 v[208:209], v85 offset0:32 offset1:48
	v_add_u32_e32 v85, 120, v84
	ds_read2st64_b32 v[210:211], v85 offset1:16
	ds_read2st64_b32 v[212:213], v85 offset0:32 offset1:48
	s_waitcnt vmcnt(31)
	v_pk_fma_f32 v[10:11], v[86:87], v[150:151], v[10:11] op_sel_hi:[0,1,1]
	v_pk_fma_f32 v[12:13], v[86:87], v[152:153], v[12:13] op_sel_hi:[0,1,1]
	global_load_dword v118, v[82:83], off nt
	v_lshl_add_u64 v[82:83], v[82:83], 0, s[14:15]
	s_waitcnt vmcnt(31)
	v_pk_fma_f32 v[10:11], v[86:87], v[154:155], v[10:11] op_sel:[1,0,0] op_sel_hi:[1,1,1]
	v_pk_fma_f32 v[12:13], v[86:87], v[156:157], v[12:13] op_sel:[1,0,0] op_sel_hi:[1,1,1]
	global_load_dword v119, v[82:83], off nt
	v_lshl_add_u64 v[82:83], v[82:83], 0, s[14:15]
	s_waitcnt vmcnt(31)
	v_pk_fma_f32 v[10:11], v[88:89], v[158:159], v[10:11] op_sel_hi:[0,1,1]
	v_pk_fma_f32 v[12:13], v[88:89], v[160:161], v[12:13] op_sel_hi:[0,1,1]
	global_load_dword v120, v[82:83], off nt
	v_lshl_add_u64 v[82:83], v[82:83], 0, s[14:15]
	s_waitcnt vmcnt(31)
	v_pk_fma_f32 v[10:11], v[88:89], v[162:163], v[10:11] op_sel:[1,0,0] op_sel_hi:[1,1,1]
	v_pk_fma_f32 v[12:13], v[88:89], v[164:165], v[12:13] op_sel:[1,0,0] op_sel_hi:[1,1,1]
	global_load_dword v121, v[82:83], off nt
	v_lshl_add_u64 v[82:83], v[82:83], 0, s[14:15]
	s_waitcnt vmcnt(31)
	v_pk_fma_f32 v[10:11], v[90:91], v[166:167], v[10:11] op_sel_hi:[0,1,1]
	v_pk_fma_f32 v[12:13], v[90:91], v[168:169], v[12:13] op_sel_hi:[0,1,1]
	global_load_dword v122, v[82:83], off nt
	v_lshl_add_u64 v[82:83], v[82:83], 0, s[14:15]
	s_waitcnt vmcnt(31)
	v_pk_fma_f32 v[10:11], v[90:91], v[170:171], v[10:11] op_sel:[1,0,0] op_sel_hi:[1,1,1]
	v_pk_fma_f32 v[12:13], v[90:91], v[172:173], v[12:13] op_sel:[1,0,0] op_sel_hi:[1,1,1]
	global_load_dword v123, v[82:83], off nt
	v_lshl_add_u64 v[82:83], v[82:83], 0, s[14:15]
	s_waitcnt vmcnt(31)
	v_pk_fma_f32 v[10:11], v[92:93], v[174:175], v[10:11] op_sel_hi:[0,1,1]
	v_pk_fma_f32 v[12:13], v[92:93], v[176:177], v[12:13] op_sel_hi:[0,1,1]
	global_load_dword v124, v[82:83], off nt
	v_lshl_add_u64 v[82:83], v[82:83], 0, s[14:15]
	s_waitcnt vmcnt(31)
	v_pk_fma_f32 v[10:11], v[92:93], v[178:179], v[10:11] op_sel:[1,0,0] op_sel_hi:[1,1,1]
	v_pk_fma_f32 v[12:13], v[92:93], v[180:181], v[12:13] op_sel:[1,0,0] op_sel_hi:[1,1,1]
	global_load_dword v125, v[82:83], off nt
	v_lshl_add_u64 v[82:83], v[82:83], 0, s[14:15]
	s_waitcnt lgkmcnt(0)
	v_add_u32_e32 v85, 128, v84
	ds_read2st64_b32 v[150:151], v85 offset1:16
	ds_read2st64_b32 v[152:153], v85 offset0:32 offset1:48
	v_add_u32_e32 v85, 136, v84
	ds_read2st64_b32 v[154:155], v85 offset1:16
	ds_read2st64_b32 v[156:157], v85 offset0:32 offset1:48
	v_add_u32_e32 v85, 144, v84
	ds_read2st64_b32 v[158:159], v85 offset1:16
	ds_read2st64_b32 v[160:161], v85 offset0:32 offset1:48
	v_add_u32_e32 v85, 152, v84
	ds_read2st64_b32 v[162:163], v85 offset1:16
	ds_read2st64_b32 v[164:165], v85 offset0:32 offset1:48
	v_add_u32_e32 v85, 160, v84
	ds_read2st64_b32 v[166:167], v85 offset1:16
	ds_read2st64_b32 v[168:169], v85 offset0:32 offset1:48
	v_add_u32_e32 v85, 168, v84
	ds_read2st64_b32 v[170:171], v85 offset1:16
	ds_read2st64_b32 v[172:173], v85 offset0:32 offset1:48
	v_add_u32_e32 v85, 176, v84
	ds_read2st64_b32 v[174:175], v85 offset1:16
	ds_read2st64_b32 v[176:177], v85 offset0:32 offset1:48
	v_add_u32_e32 v85, 184, v84
	ds_read2st64_b32 v[178:179], v85 offset1:16
	ds_read2st64_b32 v[180:181], v85 offset0:32 offset1:48
	s_waitcnt vmcnt(31)
	v_pk_fma_f32 v[10:11], v[94:95], v[182:183], v[10:11] op_sel_hi:[0,1,1]
	v_pk_fma_f32 v[12:13], v[94:95], v[184:185], v[12:13] op_sel_hi:[0,1,1]
	global_load_dword v126, v[82:83], off nt
	v_lshl_add_u64 v[82:83], v[82:83], 0, s[14:15]
	s_waitcnt vmcnt(31)
	v_pk_fma_f32 v[10:11], v[94:95], v[186:187], v[10:11] op_sel:[1,0,0] op_sel_hi:[1,1,1]
	v_pk_fma_f32 v[12:13], v[94:95], v[188:189], v[12:13] op_sel:[1,0,0] op_sel_hi:[1,1,1]
	global_load_dword v127, v[82:83], off nt
	v_lshl_add_u64 v[82:83], v[82:83], 0, s[14:15]
	s_waitcnt vmcnt(31)
	v_pk_fma_f32 v[10:11], v[96:97], v[190:191], v[10:11] op_sel_hi:[0,1,1]
	v_pk_fma_f32 v[12:13], v[96:97], v[192:193], v[12:13] op_sel_hi:[0,1,1]
	global_load_dword v128, v[82:83], off nt
	v_lshl_add_u64 v[82:83], v[82:83], 0, s[14:15]
	s_waitcnt vmcnt(31)
	v_pk_fma_f32 v[10:11], v[96:97], v[194:195], v[10:11] op_sel:[1,0,0] op_sel_hi:[1,1,1]
	v_pk_fma_f32 v[12:13], v[96:97], v[196:197], v[12:13] op_sel:[1,0,0] op_sel_hi:[1,1,1]
	global_load_dword v129, v[82:83], off nt
	v_lshl_add_u64 v[82:83], v[82:83], 0, s[14:15]
	s_waitcnt vmcnt(31)
	v_pk_fma_f32 v[10:11], v[98:99], v[198:199], v[10:11] op_sel_hi:[0,1,1]
	v_pk_fma_f32 v[12:13], v[98:99], v[200:201], v[12:13] op_sel_hi:[0,1,1]
	global_load_dword v130, v[82:83], off nt
	v_lshl_add_u64 v[82:83], v[82:83], 0, s[14:15]
	s_waitcnt vmcnt(31)
	v_pk_fma_f32 v[10:11], v[98:99], v[202:203], v[10:11] op_sel:[1,0,0] op_sel_hi:[1,1,1]
	v_pk_fma_f32 v[12:13], v[98:99], v[204:205], v[12:13] op_sel:[1,0,0] op_sel_hi:[1,1,1]
	global_load_dword v131, v[82:83], off nt
	v_lshl_add_u64 v[82:83], v[82:83], 0, s[14:15]
	s_waitcnt vmcnt(31)
	v_pk_fma_f32 v[10:11], v[100:101], v[206:207], v[10:11] op_sel_hi:[0,1,1]
	v_pk_fma_f32 v[12:13], v[100:101], v[208:209], v[12:13] op_sel_hi:[0,1,1]
	global_load_dword v132, v[82:83], off nt
	v_lshl_add_u64 v[82:83], v[82:83], 0, s[14:15]
	s_waitcnt vmcnt(31)
	v_pk_fma_f32 v[10:11], v[100:101], v[210:211], v[10:11] op_sel:[1,0,0] op_sel_hi:[1,1,1]
	v_pk_fma_f32 v[12:13], v[100:101], v[212:213], v[12:13] op_sel:[1,0,0] op_sel_hi:[1,1,1]
	global_load_dword v133, v[82:83], off nt
	v_lshl_add_u64 v[82:83], v[82:83], 0, s[14:15]
	s_waitcnt lgkmcnt(0)
	v_add_u32_e32 v85, 192, v84
	ds_read2st64_b32 v[182:183], v85 offset1:16
	ds_read2st64_b32 v[184:185], v85 offset0:32 offset1:48
	v_add_u32_e32 v85, 200, v84
	ds_read2st64_b32 v[186:187], v85 offset1:16
	ds_read2st64_b32 v[188:189], v85 offset0:32 offset1:48
	v_add_u32_e32 v85, 208, v84
	ds_read2st64_b32 v[190:191], v85 offset1:16
	ds_read2st64_b32 v[192:193], v85 offset0:32 offset1:48
	v_add_u32_e32 v85, 216, v84
	ds_read2st64_b32 v[194:195], v85 offset1:16
	ds_read2st64_b32 v[196:197], v85 offset0:32 offset1:48
	v_add_u32_e32 v85, 224, v84
	ds_read2st64_b32 v[198:199], v85 offset1:16
	ds_read2st64_b32 v[200:201], v85 offset0:32 offset1:48
	v_add_u32_e32 v85, 232, v84
	ds_read2st64_b32 v[202:203], v85 offset1:16
	ds_read2st64_b32 v[204:205], v85 offset0:32 offset1:48
	v_add_u32_e32 v85, 240, v84
	ds_read2st64_b32 v[206:207], v85 offset1:16
	ds_read2st64_b32 v[208:209], v85 offset0:32 offset1:48
	v_add_u32_e32 v85, 248, v84
	ds_read2st64_b32 v[210:211], v85 offset1:16
	ds_read2st64_b32 v[212:213], v85 offset0:32 offset1:48
	s_waitcnt vmcnt(31)
	v_pk_fma_f32 v[10:11], v[102:103], v[150:151], v[10:11] op_sel_hi:[0,1,1]
	v_pk_fma_f32 v[12:13], v[102:103], v[152:153], v[12:13] op_sel_hi:[0,1,1]
	global_load_dword v134, v[82:83], off nt
	v_lshl_add_u64 v[82:83], v[82:83], 0, s[14:15]
	s_waitcnt vmcnt(31)
	v_pk_fma_f32 v[10:11], v[102:103], v[154:155], v[10:11] op_sel:[1,0,0] op_sel_hi:[1,1,1]
	v_pk_fma_f32 v[12:13], v[102:103], v[156:157], v[12:13] op_sel:[1,0,0] op_sel_hi:[1,1,1]
	global_load_dword v135, v[82:83], off nt
	v_lshl_add_u64 v[82:83], v[82:83], 0, s[14:15]
	s_waitcnt vmcnt(31)
	v_pk_fma_f32 v[10:11], v[104:105], v[158:159], v[10:11] op_sel_hi:[0,1,1]
	v_pk_fma_f32 v[12:13], v[104:105], v[160:161], v[12:13] op_sel_hi:[0,1,1]
	global_load_dword v136, v[82:83], off nt
	v_lshl_add_u64 v[82:83], v[82:83], 0, s[14:15]
	s_waitcnt vmcnt(31)
	v_pk_fma_f32 v[10:11], v[104:105], v[162:163], v[10:11] op_sel:[1,0,0] op_sel_hi:[1,1,1]
	v_pk_fma_f32 v[12:13], v[104:105], v[164:165], v[12:13] op_sel:[1,0,0] op_sel_hi:[1,1,1]
	global_load_dword v137, v[82:83], off nt
	v_lshl_add_u64 v[82:83], v[82:83], 0, s[14:15]
	s_waitcnt vmcnt(31)
	v_pk_fma_f32 v[10:11], v[106:107], v[166:167], v[10:11] op_sel_hi:[0,1,1]
	v_pk_fma_f32 v[12:13], v[106:107], v[168:169], v[12:13] op_sel_hi:[0,1,1]
	global_load_dword v138, v[82:83], off nt
	v_lshl_add_u64 v[82:83], v[82:83], 0, s[14:15]
	s_waitcnt vmcnt(31)
	v_pk_fma_f32 v[10:11], v[106:107], v[170:171], v[10:11] op_sel:[1,0,0] op_sel_hi:[1,1,1]
	v_pk_fma_f32 v[12:13], v[106:107], v[172:173], v[12:13] op_sel:[1,0,0] op_sel_hi:[1,1,1]
	global_load_dword v139, v[82:83], off nt
	v_lshl_add_u64 v[82:83], v[82:83], 0, s[14:15]
	s_waitcnt vmcnt(31)
	v_pk_fma_f32 v[10:11], v[108:109], v[174:175], v[10:11] op_sel_hi:[0,1,1]
	v_pk_fma_f32 v[12:13], v[108:109], v[176:177], v[12:13] op_sel_hi:[0,1,1]
	global_load_dword v140, v[82:83], off nt
	v_lshl_add_u64 v[82:83], v[82:83], 0, s[14:15]
	s_waitcnt vmcnt(31)
	v_pk_fma_f32 v[10:11], v[108:109], v[178:179], v[10:11] op_sel:[1,0,0] op_sel_hi:[1,1,1]
	v_pk_fma_f32 v[12:13], v[108:109], v[180:181], v[12:13] op_sel:[1,0,0] op_sel_hi:[1,1,1]
	global_load_dword v141, v[82:83], off nt
	v_lshl_add_u64 v[82:83], v[82:83], 0, s[14:15]
	s_waitcnt lgkmcnt(0)
	v_add_u32_e32 v85, 256, v84
	ds_read2st64_b32 v[150:151], v85 offset1:16
	ds_read2st64_b32 v[152:153], v85 offset0:32 offset1:48
	v_add_u32_e32 v85, 264, v84
	ds_read2st64_b32 v[154:155], v85 offset1:16
	ds_read2st64_b32 v[156:157], v85 offset0:32 offset1:48
	v_add_u32_e32 v85, 272, v84
	ds_read2st64_b32 v[158:159], v85 offset1:16
	ds_read2st64_b32 v[160:161], v85 offset0:32 offset1:48
	v_add_u32_e32 v85, 280, v84
	ds_read2st64_b32 v[162:163], v85 offset1:16
	ds_read2st64_b32 v[164:165], v85 offset0:32 offset1:48
	v_add_u32_e32 v85, 288, v84
	ds_read2st64_b32 v[166:167], v85 offset1:16
	ds_read2st64_b32 v[168:169], v85 offset0:32 offset1:48
	v_add_u32_e32 v85, 296, v84
	ds_read2st64_b32 v[170:171], v85 offset1:16
	ds_read2st64_b32 v[172:173], v85 offset0:32 offset1:48
	v_add_u32_e32 v85, 304, v84
	ds_read2st64_b32 v[174:175], v85 offset1:16
	ds_read2st64_b32 v[176:177], v85 offset0:32 offset1:48
	v_add_u32_e32 v85, 312, v84
	ds_read2st64_b32 v[178:179], v85 offset1:16
	ds_read2st64_b32 v[180:181], v85 offset0:32 offset1:48
	s_waitcnt vmcnt(31)
	v_pk_fma_f32 v[10:11], v[110:111], v[182:183], v[10:11] op_sel_hi:[0,1,1]
	v_pk_fma_f32 v[12:13], v[110:111], v[184:185], v[12:13] op_sel_hi:[0,1,1]
	global_load_dword v142, v[82:83], off nt
	v_lshl_add_u64 v[82:83], v[82:83], 0, s[14:15]
	s_waitcnt vmcnt(31)
	v_pk_fma_f32 v[10:11], v[110:111], v[186:187], v[10:11] op_sel:[1,0,0] op_sel_hi:[1,1,1]
	v_pk_fma_f32 v[12:13], v[110:111], v[188:189], v[12:13] op_sel:[1,0,0] op_sel_hi:[1,1,1]
	global_load_dword v143, v[82:83], off nt
	v_lshl_add_u64 v[82:83], v[82:83], 0, s[14:15]
	s_waitcnt vmcnt(31)
	v_pk_fma_f32 v[10:11], v[112:113], v[190:191], v[10:11] op_sel_hi:[0,1,1]
	v_pk_fma_f32 v[12:13], v[112:113], v[192:193], v[12:13] op_sel_hi:[0,1,1]
	global_load_dword v144, v[82:83], off nt
	v_lshl_add_u64 v[82:83], v[82:83], 0, s[14:15]
	s_waitcnt vmcnt(31)
	v_pk_fma_f32 v[10:11], v[112:113], v[194:195], v[10:11] op_sel:[1,0,0] op_sel_hi:[1,1,1]
	v_pk_fma_f32 v[12:13], v[112:113], v[196:197], v[12:13] op_sel:[1,0,0] op_sel_hi:[1,1,1]
	global_load_dword v145, v[82:83], off nt
	v_lshl_add_u64 v[82:83], v[82:83], 0, s[14:15]
	s_waitcnt vmcnt(31)
	v_pk_fma_f32 v[10:11], v[114:115], v[198:199], v[10:11] op_sel_hi:[0,1,1]
	v_pk_fma_f32 v[12:13], v[114:115], v[200:201], v[12:13] op_sel_hi:[0,1,1]
	global_load_dword v146, v[82:83], off nt
	v_lshl_add_u64 v[82:83], v[82:83], 0, s[14:15]
	s_waitcnt vmcnt(31)
	v_pk_fma_f32 v[10:11], v[114:115], v[202:203], v[10:11] op_sel:[1,0,0] op_sel_hi:[1,1,1]
	v_pk_fma_f32 v[12:13], v[114:115], v[204:205], v[12:13] op_sel:[1,0,0] op_sel_hi:[1,1,1]
	global_load_dword v147, v[82:83], off nt
	v_lshl_add_u64 v[82:83], v[82:83], 0, s[14:15]
	s_waitcnt vmcnt(31)
	v_pk_fma_f32 v[10:11], v[116:117], v[206:207], v[10:11] op_sel_hi:[0,1,1]
	v_pk_fma_f32 v[12:13], v[116:117], v[208:209], v[12:13] op_sel_hi:[0,1,1]
	global_load_dword v148, v[82:83], off nt
	v_lshl_add_u64 v[82:83], v[82:83], 0, s[14:15]
	s_waitcnt vmcnt(31)
	v_pk_fma_f32 v[10:11], v[116:117], v[210:211], v[10:11] op_sel:[1,0,0] op_sel_hi:[1,1,1]
	v_pk_fma_f32 v[12:13], v[116:117], v[212:213], v[12:13] op_sel:[1,0,0] op_sel_hi:[1,1,1]
	global_load_dword v149, v[82:83], off nt
	v_lshl_add_u64 v[82:83], v[82:83], 0, s[14:15]
	s_waitcnt lgkmcnt(0)
	v_add_u32_e32 v85, 320, v84
	ds_read2st64_b32 v[182:183], v85 offset1:16
	ds_read2st64_b32 v[184:185], v85 offset0:32 offset1:48
	v_add_u32_e32 v85, 328, v84
	ds_read2st64_b32 v[186:187], v85 offset1:16
	ds_read2st64_b32 v[188:189], v85 offset0:32 offset1:48
	v_add_u32_e32 v85, 336, v84
	ds_read2st64_b32 v[190:191], v85 offset1:16
	ds_read2st64_b32 v[192:193], v85 offset0:32 offset1:48
	v_add_u32_e32 v85, 344, v84
	ds_read2st64_b32 v[194:195], v85 offset1:16
	ds_read2st64_b32 v[196:197], v85 offset0:32 offset1:48
	v_add_u32_e32 v85, 352, v84
	ds_read2st64_b32 v[198:199], v85 offset1:16
	ds_read2st64_b32 v[200:201], v85 offset0:32 offset1:48
	v_add_u32_e32 v85, 360, v84
	ds_read2st64_b32 v[202:203], v85 offset1:16
	ds_read2st64_b32 v[204:205], v85 offset0:32 offset1:48
	v_add_u32_e32 v85, 368, v84
	ds_read2st64_b32 v[206:207], v85 offset1:16
	ds_read2st64_b32 v[208:209], v85 offset0:32 offset1:48
	v_add_u32_e32 v85, 376, v84
	ds_read2st64_b32 v[210:211], v85 offset1:16
	ds_read2st64_b32 v[212:213], v85 offset0:32 offset1:48
	s_waitcnt vmcnt(31)
	v_pk_fma_f32 v[10:11], v[118:119], v[150:151], v[10:11] op_sel_hi:[0,1,1]
	v_pk_fma_f32 v[12:13], v[118:119], v[152:153], v[12:13] op_sel_hi:[0,1,1]
	s_waitcnt vmcnt(30)
	v_pk_fma_f32 v[10:11], v[118:119], v[154:155], v[10:11] op_sel:[1,0,0] op_sel_hi:[1,1,1]
	v_pk_fma_f32 v[12:13], v[118:119], v[156:157], v[12:13] op_sel:[1,0,0] op_sel_hi:[1,1,1]
	s_waitcnt vmcnt(29)
	v_pk_fma_f32 v[10:11], v[120:121], v[158:159], v[10:11] op_sel_hi:[0,1,1]
	v_pk_fma_f32 v[12:13], v[120:121], v[160:161], v[12:13] op_sel_hi:[0,1,1]
	s_waitcnt vmcnt(28)
	v_pk_fma_f32 v[10:11], v[120:121], v[162:163], v[10:11] op_sel:[1,0,0] op_sel_hi:[1,1,1]
	v_pk_fma_f32 v[12:13], v[120:121], v[164:165], v[12:13] op_sel:[1,0,0] op_sel_hi:[1,1,1]
	s_waitcnt vmcnt(27)
	v_pk_fma_f32 v[10:11], v[122:123], v[166:167], v[10:11] op_sel_hi:[0,1,1]
	v_pk_fma_f32 v[12:13], v[122:123], v[168:169], v[12:13] op_sel_hi:[0,1,1]
	s_waitcnt vmcnt(26)
	v_pk_fma_f32 v[10:11], v[122:123], v[170:171], v[10:11] op_sel:[1,0,0] op_sel_hi:[1,1,1]
	v_pk_fma_f32 v[12:13], v[122:123], v[172:173], v[12:13] op_sel:[1,0,0] op_sel_hi:[1,1,1]
	s_waitcnt vmcnt(25)
	v_pk_fma_f32 v[10:11], v[124:125], v[174:175], v[10:11] op_sel_hi:[0,1,1]
	v_pk_fma_f32 v[12:13], v[124:125], v[176:177], v[12:13] op_sel_hi:[0,1,1]
	s_waitcnt vmcnt(24)
	v_pk_fma_f32 v[10:11], v[124:125], v[178:179], v[10:11] op_sel:[1,0,0] op_sel_hi:[1,1,1]
	v_pk_fma_f32 v[12:13], v[124:125], v[180:181], v[12:13] op_sel:[1,0,0] op_sel_hi:[1,1,1]
	s_waitcnt lgkmcnt(0)
	v_add_u32_e32 v85, 384, v84
	ds_read2st64_b32 v[150:151], v85 offset1:16
	ds_read2st64_b32 v[152:153], v85 offset0:32 offset1:48
	v_add_u32_e32 v85, 392, v84
	ds_read2st64_b32 v[154:155], v85 offset1:16
	ds_read2st64_b32 v[156:157], v85 offset0:32 offset1:48
	v_add_u32_e32 v85, 400, v84
	ds_read2st64_b32 v[158:159], v85 offset1:16
	ds_read2st64_b32 v[160:161], v85 offset0:32 offset1:48
	v_add_u32_e32 v85, 408, v84
	ds_read2st64_b32 v[162:163], v85 offset1:16
	ds_read2st64_b32 v[164:165], v85 offset0:32 offset1:48
	v_add_u32_e32 v85, 416, v84
	ds_read2st64_b32 v[166:167], v85 offset1:16
	ds_read2st64_b32 v[168:169], v85 offset0:32 offset1:48
	v_add_u32_e32 v85, 424, v84
	ds_read2st64_b32 v[170:171], v85 offset1:16
	ds_read2st64_b32 v[172:173], v85 offset0:32 offset1:48
	v_add_u32_e32 v85, 432, v84
	ds_read2st64_b32 v[174:175], v85 offset1:16
	ds_read2st64_b32 v[176:177], v85 offset0:32 offset1:48
	v_add_u32_e32 v85, 440, v84
	ds_read2st64_b32 v[178:179], v85 offset1:16
	ds_read2st64_b32 v[180:181], v85 offset0:32 offset1:48
	s_waitcnt vmcnt(23)
	v_pk_fma_f32 v[10:11], v[126:127], v[182:183], v[10:11] op_sel_hi:[0,1,1]
	v_pk_fma_f32 v[12:13], v[126:127], v[184:185], v[12:13] op_sel_hi:[0,1,1]
	s_waitcnt vmcnt(22)
	v_pk_fma_f32 v[10:11], v[126:127], v[186:187], v[10:11] op_sel:[1,0,0] op_sel_hi:[1,1,1]
	v_pk_fma_f32 v[12:13], v[126:127], v[188:189], v[12:13] op_sel:[1,0,0] op_sel_hi:[1,1,1]
	s_waitcnt vmcnt(21)
	v_pk_fma_f32 v[10:11], v[128:129], v[190:191], v[10:11] op_sel_hi:[0,1,1]
	v_pk_fma_f32 v[12:13], v[128:129], v[192:193], v[12:13] op_sel_hi:[0,1,1]
	s_waitcnt vmcnt(20)
	v_pk_fma_f32 v[10:11], v[128:129], v[194:195], v[10:11] op_sel:[1,0,0] op_sel_hi:[1,1,1]
	v_pk_fma_f32 v[12:13], v[128:129], v[196:197], v[12:13] op_sel:[1,0,0] op_sel_hi:[1,1,1]
	s_waitcnt vmcnt(19)
	v_pk_fma_f32 v[10:11], v[130:131], v[198:199], v[10:11] op_sel_hi:[0,1,1]
	v_pk_fma_f32 v[12:13], v[130:131], v[200:201], v[12:13] op_sel_hi:[0,1,1]
	s_waitcnt vmcnt(18)
	v_pk_fma_f32 v[10:11], v[130:131], v[202:203], v[10:11] op_sel:[1,0,0] op_sel_hi:[1,1,1]
	v_pk_fma_f32 v[12:13], v[130:131], v[204:205], v[12:13] op_sel:[1,0,0] op_sel_hi:[1,1,1]
	s_waitcnt vmcnt(17)
	v_pk_fma_f32 v[10:11], v[132:133], v[206:207], v[10:11] op_sel_hi:[0,1,1]
	v_pk_fma_f32 v[12:13], v[132:133], v[208:209], v[12:13] op_sel_hi:[0,1,1]
	s_waitcnt vmcnt(16)
	v_pk_fma_f32 v[10:11], v[132:133], v[210:211], v[10:11] op_sel:[1,0,0] op_sel_hi:[1,1,1]
	v_pk_fma_f32 v[12:13], v[132:133], v[212:213], v[12:13] op_sel:[1,0,0] op_sel_hi:[1,1,1]
	s_waitcnt lgkmcnt(0)
	v_add_u32_e32 v85, 448, v84
	ds_read2st64_b32 v[182:183], v85 offset1:16
	ds_read2st64_b32 v[184:185], v85 offset0:32 offset1:48
	v_add_u32_e32 v85, 456, v84
	ds_read2st64_b32 v[186:187], v85 offset1:16
	ds_read2st64_b32 v[188:189], v85 offset0:32 offset1:48
	v_add_u32_e32 v85, 464, v84
	ds_read2st64_b32 v[190:191], v85 offset1:16
	ds_read2st64_b32 v[192:193], v85 offset0:32 offset1:48
	v_add_u32_e32 v85, 472, v84
	ds_read2st64_b32 v[194:195], v85 offset1:16
	ds_read2st64_b32 v[196:197], v85 offset0:32 offset1:48
	v_add_u32_e32 v85, 480, v84
	ds_read2st64_b32 v[198:199], v85 offset1:16
	ds_read2st64_b32 v[200:201], v85 offset0:32 offset1:48
	v_add_u32_e32 v85, 488, v84
	ds_read2st64_b32 v[202:203], v85 offset1:16
	ds_read2st64_b32 v[204:205], v85 offset0:32 offset1:48
	v_add_u32_e32 v85, 496, v84
	ds_read2st64_b32 v[206:207], v85 offset1:16
	ds_read2st64_b32 v[208:209], v85 offset0:32 offset1:48
	v_add_u32_e32 v85, 504, v84
	ds_read2st64_b32 v[210:211], v85 offset1:16
	ds_read2st64_b32 v[212:213], v85 offset0:32 offset1:48
	s_waitcnt vmcnt(15)
	v_pk_fma_f32 v[10:11], v[134:135], v[150:151], v[10:11] op_sel_hi:[0,1,1]
	v_pk_fma_f32 v[12:13], v[134:135], v[152:153], v[12:13] op_sel_hi:[0,1,1]
	s_waitcnt vmcnt(14)
	v_pk_fma_f32 v[10:11], v[134:135], v[154:155], v[10:11] op_sel:[1,0,0] op_sel_hi:[1,1,1]
	v_pk_fma_f32 v[12:13], v[134:135], v[156:157], v[12:13] op_sel:[1,0,0] op_sel_hi:[1,1,1]
	s_waitcnt vmcnt(13)
	v_pk_fma_f32 v[10:11], v[136:137], v[158:159], v[10:11] op_sel_hi:[0,1,1]
	v_pk_fma_f32 v[12:13], v[136:137], v[160:161], v[12:13] op_sel_hi:[0,1,1]
	s_waitcnt vmcnt(12)
	v_pk_fma_f32 v[10:11], v[136:137], v[162:163], v[10:11] op_sel:[1,0,0] op_sel_hi:[1,1,1]
	v_pk_fma_f32 v[12:13], v[136:137], v[164:165], v[12:13] op_sel:[1,0,0] op_sel_hi:[1,1,1]
	s_waitcnt vmcnt(11)
	v_pk_fma_f32 v[10:11], v[138:139], v[166:167], v[10:11] op_sel_hi:[0,1,1]
	v_pk_fma_f32 v[12:13], v[138:139], v[168:169], v[12:13] op_sel_hi:[0,1,1]
	s_waitcnt vmcnt(10)
	v_pk_fma_f32 v[10:11], v[138:139], v[170:171], v[10:11] op_sel:[1,0,0] op_sel_hi:[1,1,1]
	v_pk_fma_f32 v[12:13], v[138:139], v[172:173], v[12:13] op_sel:[1,0,0] op_sel_hi:[1,1,1]
	s_waitcnt vmcnt(9)
	v_pk_fma_f32 v[10:11], v[140:141], v[174:175], v[10:11] op_sel_hi:[0,1,1]
	v_pk_fma_f32 v[12:13], v[140:141], v[176:177], v[12:13] op_sel_hi:[0,1,1]
	s_waitcnt vmcnt(8)
	v_pk_fma_f32 v[10:11], v[140:141], v[178:179], v[10:11] op_sel:[1,0,0] op_sel_hi:[1,1,1]
	v_pk_fma_f32 v[12:13], v[140:141], v[180:181], v[12:13] op_sel:[1,0,0] op_sel_hi:[1,1,1]
	s_waitcnt lgkmcnt(0)
	s_waitcnt vmcnt(7)
	v_pk_fma_f32 v[10:11], v[142:143], v[182:183], v[10:11] op_sel_hi:[0,1,1]
	v_pk_fma_f32 v[12:13], v[142:143], v[184:185], v[12:13] op_sel_hi:[0,1,1]
	s_waitcnt vmcnt(6)
	v_pk_fma_f32 v[10:11], v[142:143], v[186:187], v[10:11] op_sel:[1,0,0] op_sel_hi:[1,1,1]
	v_pk_fma_f32 v[12:13], v[142:143], v[188:189], v[12:13] op_sel:[1,0,0] op_sel_hi:[1,1,1]
	s_waitcnt vmcnt(5)
	v_pk_fma_f32 v[10:11], v[144:145], v[190:191], v[10:11] op_sel_hi:[0,1,1]
	v_pk_fma_f32 v[12:13], v[144:145], v[192:193], v[12:13] op_sel_hi:[0,1,1]
	s_waitcnt vmcnt(4)
	v_pk_fma_f32 v[10:11], v[144:145], v[194:195], v[10:11] op_sel:[1,0,0] op_sel_hi:[1,1,1]
	v_pk_fma_f32 v[12:13], v[144:145], v[196:197], v[12:13] op_sel:[1,0,0] op_sel_hi:[1,1,1]
	s_waitcnt vmcnt(3)
	v_pk_fma_f32 v[10:11], v[146:147], v[198:199], v[10:11] op_sel_hi:[0,1,1]
	v_pk_fma_f32 v[12:13], v[146:147], v[200:201], v[12:13] op_sel_hi:[0,1,1]
	s_waitcnt vmcnt(2)
	v_pk_fma_f32 v[10:11], v[146:147], v[202:203], v[10:11] op_sel:[1,0,0] op_sel_hi:[1,1,1]
	v_pk_fma_f32 v[12:13], v[146:147], v[204:205], v[12:13] op_sel:[1,0,0] op_sel_hi:[1,1,1]
	s_waitcnt vmcnt(1)
	v_pk_fma_f32 v[10:11], v[148:149], v[206:207], v[10:11] op_sel_hi:[0,1,1]
	v_pk_fma_f32 v[12:13], v[148:149], v[208:209], v[12:13] op_sel_hi:[0,1,1]
	s_waitcnt vmcnt(0)
	v_pk_fma_f32 v[10:11], v[148:149], v[210:211], v[10:11] op_sel:[1,0,0] op_sel_hi:[1,1,1]
	v_pk_fma_f32 v[12:13], v[148:149], v[212:213], v[12:13] op_sel:[1,0,0] op_sel_hi:[1,1,1]
